# adds: removed the 16 redundant mid-block s_setprio 0/1 toggle pairs inside the GEMM MFMA blocks
# speedup vs baseline: 1.0217x; 1.0015x over previous
.LBB0_68:
	s_add_u32 s24, s22, 0xfffc0080
	s_addc_u32 s25, s23, -1
	s_add_i32 s60, 0, 0x10000
	s_cmp_eq_u32 s57, 12
	s_cselect_b32 s27, s15, s25
	s_cselect_b32 s26, s21, s24
	s_cselect_b32 s25, s13, s56
	s_cselect_b32 s24, s33, s55
	s_add_i32 s63, 0, 0x14000
	v_add_u32_e32 v154, s60, v172
	v_add_u32_e32 v176, s63, v172
	ds_read_b128 v[130:133], v154
	ds_read_b128 v[146:149], v154 offset:1024
	ds_read_b128 v[150:153], v154 offset:2048
	ds_read_b128 v[154:157], v154 offset:3072
	ds_read_b128 v[158:161], v176
	ds_read_b128 v[162:165], v176 offset:1024
	ds_read_b128 v[168:171], v176 offset:2048
	ds_read_b128 v[176:179], v176 offset:3072
	v_lshl_add_u64 v[208:209], s[22:23], 0, v[142:143]
	s_add_i32 m0, s37, 0xc000
	ds_read_b128 v[180:183], v175
	ds_read_b128 v[184:187], v175 offset:1024
	ds_read_b128 v[188:191], v175 offset:2048
	ds_read_b128 v[192:195], v175 offset:3072
	ds_read_b128 v[196:199], v175 offset:4096
	ds_read_b128 v[200:203], v175 offset:5120
	ds_read_b128 v[204:207], v175 offset:6144
	ds_read_b128 v[216:219], v175 offset:7168
	global_load_lds_dwordx4 v[208:209], off
	v_lshl_add_u64 v[208:209], s[22:23], 0, v[144:145]
	s_add_i32 m0, s37, 0xe000
	s_nop 0
	global_load_lds_dwordx4 v[208:209], off
	s_waitcnt vmcnt(8)
	s_waitcnt lgkmcnt(0)
	s_barrier
	s_setprio 1
	s_waitcnt lgkmcnt(0)
	v_mfma_f32_16x16x32_f16 v[126:129], v[130:133], v[180:183], v[126:129]
	v_mfma_f32_16x16x32_f16 v[118:121], v[150:153], v[180:183], v[118:121]
	v_mfma_f32_16x16x32_f16 v[110:113], v[130:133], v[188:191], v[110:113]
	v_mfma_f32_16x16x32_f16 v[102:105], v[150:153], v[188:191], v[102:105]
	v_mfma_f32_16x16x32_f16 v[92:95], v[130:133], v[196:199], v[92:95]
	v_mfma_f32_16x16x32_f16 v[84:87], v[150:153], v[196:199], v[84:87]
	v_mfma_f32_16x16x32_f16 v[76:79], v[130:133], v[204:207], v[76:79]
	v_mfma_f32_16x16x32_f16 v[68:71], v[150:153], v[204:207], v[68:71]
	v_mfma_f32_16x16x32_f16 v[126:129], v[146:149], v[184:187], v[126:129]
	v_mfma_f32_16x16x32_f16 v[118:121], v[154:157], v[184:187], v[118:121]
	v_mfma_f32_16x16x32_f16 v[110:113], v[146:149], v[192:195], v[110:113]
	v_mfma_f32_16x16x32_f16 v[102:105], v[154:157], v[192:195], v[102:105]
	v_mfma_f32_16x16x32_f16 v[92:95], v[146:149], v[200:203], v[92:95]
	v_mfma_f32_16x16x32_f16 v[84:87], v[154:157], v[200:203], v[84:87]
	v_mfma_f32_16x16x32_f16 v[76:79], v[146:149], v[216:219], v[76:79]
	v_mfma_f32_16x16x32_f16 v[68:71], v[154:157], v[216:219], v[68:71]
	v_mfma_f32_16x16x32_f16 v[122:125], v[158:161], v[180:183], v[122:125]
	v_mfma_f32_16x16x32_f16 v[114:117], v[168:171], v[180:183], v[114:117]
	v_mfma_f32_16x16x32_f16 v[106:109], v[158:161], v[188:191], v[106:109]
	v_mfma_f32_16x16x32_f16 v[98:101], v[168:171], v[188:191], v[98:101]
	v_mfma_f32_16x16x32_f16 v[88:91], v[158:161], v[196:199], v[88:91]
	v_mfma_f32_16x16x32_f16 v[80:83], v[168:171], v[196:199], v[80:83]
	v_mfma_f32_16x16x32_f16 v[72:75], v[158:161], v[204:207], v[72:75]
	v_mfma_f32_16x16x32_f16 v[64:67], v[168:171], v[204:207], v[64:67]
	v_mfma_f32_16x16x32_f16 v[122:125], v[162:165], v[184:187], v[122:125]
	v_mfma_f32_16x16x32_f16 v[114:117], v[176:179], v[184:187], v[114:117]
	v_mfma_f32_16x16x32_f16 v[106:109], v[162:165], v[192:195], v[106:109]
	v_mfma_f32_16x16x32_f16 v[98:101], v[176:179], v[192:195], v[98:101]
	v_mfma_f32_16x16x32_f16 v[88:91], v[162:165], v[200:203], v[88:91]
	v_mfma_f32_16x16x32_f16 v[80:83], v[176:179], v[200:203], v[80:83]
	v_mfma_f32_16x16x32_f16 v[72:75], v[162:165], v[216:219], v[72:75]
	v_mfma_f32_16x16x32_f16 v[64:67], v[176:179], v[216:219], v[64:67]
	s_setprio 0
	s_barrier
	s_add_i32 s60, s60, s29
	v_lshl_add_u64 v[208:209], s[24:25], 0, v[96:97]
	s_mov_b32 m0, s60
	ds_read_b128 v[180:183], v175 offset:16384
	ds_read_b128 v[184:187], v175 offset:17408
	ds_read_b128 v[188:191], v175 offset:18432
	ds_read_b128 v[192:195], v175 offset:19456
	ds_read_b128 v[196:199], v175 offset:20480
	ds_read_b128 v[200:203], v175 offset:21504
	ds_read_b128 v[204:207], v175 offset:22528
	ds_read_b128 v[216:219], v175 offset:23552
	global_load_lds_dwordx4 v[208:209], off
	s_add_i32 m0, s60, 0x2000
	s_add_u32 s60, s24, 0x40000
	v_lshl_add_u64 v[210:211], s[24:25], 0, v[134:135]
	s_addc_u32 s61, s25, 0
	s_add_i32 s63, s63, s29
	global_load_lds_dwordx4 v[210:211], off
	v_lshl_add_u64 v[212:213], s[60:61], 0, v[96:97]
	s_mov_b32 m0, s63
	v_lshl_add_u64 v[220:221], s[26:27], 0, v[136:137]
	global_load_lds_dwordx4 v[212:213], off
	v_lshl_add_u64 v[212:213], s[60:61], 0, v[134:135]
	s_add_i32 m0, s63, 0x2000
	s_nop 0
	global_load_lds_dwordx4 v[212:213], off
	v_lshl_add_u64 v[212:213], s[26:27], 0, v[138:139]
	s_mov_b32 m0, s37
	s_nop 0
	global_load_lds_dwordx4 v[212:213], off
	s_mov_b32 m0, s45
	s_nop 0
	global_load_lds_dwordx4 v[220:221], off
	s_waitcnt vmcnt(8)
	s_waitcnt lgkmcnt(0)
	s_barrier
	s_setprio 1
	s_waitcnt lgkmcnt(0)
	v_mfma_f32_16x16x32_f16 v[60:63], v[130:133], v[180:183], v[60:63]
	v_mfma_f32_16x16x32_f16 v[52:55], v[150:153], v[180:183], v[52:55]
	v_mfma_f32_16x16x32_f16 v[44:47], v[130:133], v[188:191], v[44:47]
	v_mfma_f32_16x16x32_f16 v[36:39], v[150:153], v[188:191], v[36:39]
	v_mfma_f32_16x16x32_f16 v[28:31], v[130:133], v[196:199], v[28:31]
	v_mfma_f32_16x16x32_f16 v[20:23], v[150:153], v[196:199], v[20:23]
	v_mfma_f32_16x16x32_f16 v[12:15], v[130:133], v[204:207], v[12:15]
	v_mfma_f32_16x16x32_f16 v[4:7], v[150:153], v[204:207], v[4:7]
	v_mfma_f32_16x16x32_f16 v[60:63], v[146:149], v[184:187], v[60:63]
	v_mfma_f32_16x16x32_f16 v[52:55], v[154:157], v[184:187], v[52:55]
	v_mfma_f32_16x16x32_f16 v[44:47], v[146:149], v[192:195], v[44:47]
	v_mfma_f32_16x16x32_f16 v[36:39], v[154:157], v[192:195], v[36:39]
	v_mfma_f32_16x16x32_f16 v[28:31], v[146:149], v[200:203], v[28:31]
	v_mfma_f32_16x16x32_f16 v[20:23], v[154:157], v[200:203], v[20:23]
	v_mfma_f32_16x16x32_f16 v[12:15], v[146:149], v[216:219], v[12:15]
	v_mfma_f32_16x16x32_f16 v[4:7], v[154:157], v[216:219], v[4:7]
	v_mfma_f32_16x16x32_f16 v[56:59], v[158:161], v[180:183], v[56:59]
	v_mfma_f32_16x16x32_f16 v[48:51], v[168:171], v[180:183], v[48:51]
	v_mfma_f32_16x16x32_f16 v[40:43], v[158:161], v[188:191], v[40:43]
	v_mfma_f32_16x16x32_f16 v[32:35], v[168:171], v[188:191], v[32:35]
	v_mfma_f32_16x16x32_f16 v[24:27], v[158:161], v[196:199], v[24:27]
	v_mfma_f32_16x16x32_f16 v[16:19], v[168:171], v[196:199], v[16:19]
	v_mfma_f32_16x16x32_f16 v[8:11], v[158:161], v[204:207], v[8:11]
	v_mfma_f32_16x16x32_f16 v[0:3], v[168:171], v[204:207], v[0:3]
	v_mfma_f32_16x16x32_f16 v[56:59], v[162:165], v[184:187], v[56:59]
	v_mfma_f32_16x16x32_f16 v[48:51], v[176:179], v[184:187], v[48:51]
	v_mfma_f32_16x16x32_f16 v[40:43], v[162:165], v[192:195], v[40:43]
	v_mfma_f32_16x16x32_f16 v[32:35], v[176:179], v[192:195], v[32:35]
	v_mfma_f32_16x16x32_f16 v[24:27], v[162:165], v[200:203], v[24:27]
	v_mfma_f32_16x16x32_f16 v[16:19], v[176:179], v[200:203], v[16:19]
	v_mfma_f32_16x16x32_f16 v[8:11], v[162:165], v[216:219], v[8:11]
	v_mfma_f32_16x16x32_f16 v[0:3], v[176:179], v[216:219], v[0:3]
	s_setprio 0
	s_barrier
	s_add_i32 s60, 0, 0x18000
	s_add_i32 s61, 0, 0x1c000
	v_add_u32_e32 v154, s60, v172
	v_add_u32_e32 v176, s61, v172
	ds_read_b128 v[130:133], v154
	ds_read_b128 v[146:149], v154 offset:1024
	ds_read_b128 v[150:153], v154 offset:2048
	ds_read_b128 v[154:157], v154 offset:3072
	ds_read_b128 v[158:161], v176
	ds_read_b128 v[162:165], v176 offset:1024
	ds_read_b128 v[168:171], v176 offset:2048
	ds_read_b128 v[176:179], v176 offset:3072
	s_add_u32 s26, s26, 0x40000
	s_addc_u32 s27, s27, 0
	s_mov_b32 m0, s46
	v_lshl_add_u64 v[222:223], s[26:27], 0, v[138:139]
	ds_read_b128 v[180:183], v175 offset:32768
	ds_read_b128 v[184:187], v175 offset:33792
	ds_read_b128 v[188:191], v175 offset:34816
	ds_read_b128 v[192:195], v175 offset:35840
	ds_read_b128 v[196:199], v175 offset:36864
	ds_read_b128 v[200:203], v175 offset:37888
	ds_read_b128 v[204:207], v175 offset:38912
	ds_read_b128 v[216:219], v175 offset:39936
	global_load_lds_dwordx4 v[222:223], off
	v_lshl_add_u64 v[222:223], s[26:27], 0, v[136:137]
	s_mov_b32 m0, s47
	s_nop 0
	global_load_lds_dwordx4 v[222:223], off
	s_waitcnt vmcnt(8)
	s_waitcnt lgkmcnt(0)
	s_barrier
	s_setprio 1
	s_waitcnt lgkmcnt(0)
	v_mfma_f32_16x16x32_f16 v[126:129], v[130:133], v[180:183], v[126:129]
	v_mfma_f32_16x16x32_f16 v[118:121], v[150:153], v[180:183], v[118:121]
	v_mfma_f32_16x16x32_f16 v[110:113], v[130:133], v[188:191], v[110:113]
	v_mfma_f32_16x16x32_f16 v[102:105], v[150:153], v[188:191], v[102:105]
	v_mfma_f32_16x16x32_f16 v[92:95], v[130:133], v[196:199], v[92:95]
	v_mfma_f32_16x16x32_f16 v[84:87], v[150:153], v[196:199], v[84:87]
	v_mfma_f32_16x16x32_f16 v[76:79], v[130:133], v[204:207], v[76:79]
	v_mfma_f32_16x16x32_f16 v[68:71], v[150:153], v[204:207], v[68:71]
	v_mfma_f32_16x16x32_f16 v[126:129], v[146:149], v[184:187], v[126:129]
	v_mfma_f32_16x16x32_f16 v[118:121], v[154:157], v[184:187], v[118:121]
	v_mfma_f32_16x16x32_f16 v[110:113], v[146:149], v[192:195], v[110:113]
	v_mfma_f32_16x16x32_f16 v[102:105], v[154:157], v[192:195], v[102:105]
	v_mfma_f32_16x16x32_f16 v[92:95], v[146:149], v[200:203], v[92:95]
	v_mfma_f32_16x16x32_f16 v[84:87], v[154:157], v[200:203], v[84:87]
	v_mfma_f32_16x16x32_f16 v[76:79], v[146:149], v[216:219], v[76:79]
	v_mfma_f32_16x16x32_f16 v[68:71], v[154:157], v[216:219], v[68:71]
	v_mfma_f32_16x16x32_f16 v[122:125], v[158:161], v[180:183], v[122:125]
	v_mfma_f32_16x16x32_f16 v[114:117], v[168:171], v[180:183], v[114:117]
	v_mfma_f32_16x16x32_f16 v[106:109], v[158:161], v[188:191], v[106:109]
	v_mfma_f32_16x16x32_f16 v[98:101], v[168:171], v[188:191], v[98:101]
	v_mfma_f32_16x16x32_f16 v[88:91], v[158:161], v[196:199], v[88:91]
	v_mfma_f32_16x16x32_f16 v[80:83], v[168:171], v[196:199], v[80:83]
	v_mfma_f32_16x16x32_f16 v[72:75], v[158:161], v[204:207], v[72:75]
	v_mfma_f32_16x16x32_f16 v[64:67], v[168:171], v[204:207], v[64:67]
	v_mfma_f32_16x16x32_f16 v[122:125], v[162:165], v[184:187], v[122:125]
	v_mfma_f32_16x16x32_f16 v[114:117], v[176:179], v[184:187], v[114:117]
	v_mfma_f32_16x16x32_f16 v[106:109], v[162:165], v[192:195], v[106:109]
	v_mfma_f32_16x16x32_f16 v[98:101], v[176:179], v[192:195], v[98:101]
	v_mfma_f32_16x16x32_f16 v[88:91], v[162:165], v[200:203], v[88:91]
	v_mfma_f32_16x16x32_f16 v[80:83], v[176:179], v[200:203], v[80:83]
	v_mfma_f32_16x16x32_f16 v[72:75], v[162:165], v[216:219], v[72:75]
	v_mfma_f32_16x16x32_f16 v[64:67], v[176:179], v[216:219], v[64:67]
	s_setprio 0
	s_barrier
	s_add_i32 s26, s60, s29
	v_lshl_add_u64 v[208:209], v[208:209], 0, s[94:95]
	s_mov_b32 m0, s26
	ds_read_b128 v[180:183], v175 offset:49152
	ds_read_b128 v[184:187], v175 offset:50176
	ds_read_b128 v[188:191], v175 offset:51200
	ds_read_b128 v[192:195], v175 offset:52224
	ds_read_b128 v[196:199], v175 offset:53248
	ds_read_b128 v[200:203], v175 offset:54272
	ds_read_b128 v[204:207], v175 offset:55296
	ds_read_b128 v[216:219], v175 offset:56320
	global_load_lds_dwordx4 v[208:209], off
	s_add_i32 m0, s26, 0x2000
	s_add_u32 s24, s24, 0x40080
	v_lshl_add_u64 v[208:209], v[210:211], 0, s[94:95]
	s_addc_u32 s25, s25, 0
	s_add_i32 s26, s61, s29
	global_load_lds_dwordx4 v[208:209], off
	v_lshl_add_u64 v[208:209], s[24:25], 0, v[96:97]
	s_mov_b32 m0, s26
	s_nop 0
	global_load_lds_dwordx4 v[208:209], off
	v_lshl_add_u64 v[208:209], s[24:25], 0, v[134:135]
	s_add_i32 m0, s26, 0x2000
	s_nop 0
	global_load_lds_dwordx4 v[208:209], off
	v_lshl_add_u64 v[208:209], v[212:213], 0, s[94:95]
	s_mov_b32 m0, s48
	s_nop 0
	global_load_lds_dwordx4 v[208:209], off
	v_lshl_add_u64 v[208:209], v[220:221], 0, s[94:95]
	s_mov_b32 m0, s49
	s_nop 0
	global_load_lds_dwordx4 v[208:209], off
	s_waitcnt vmcnt(8)
	s_waitcnt lgkmcnt(0)
	s_barrier
	s_setprio 1
	s_waitcnt lgkmcnt(0)
	v_mfma_f32_16x16x32_f16 v[60:63], v[130:133], v[180:183], v[60:63]
	v_mfma_f32_16x16x32_f16 v[52:55], v[150:153], v[180:183], v[52:55]
	v_mfma_f32_16x16x32_f16 v[44:47], v[130:133], v[188:191], v[44:47]
	v_mfma_f32_16x16x32_f16 v[36:39], v[150:153], v[188:191], v[36:39]
	v_mfma_f32_16x16x32_f16 v[28:31], v[130:133], v[196:199], v[28:31]
	v_mfma_f32_16x16x32_f16 v[20:23], v[150:153], v[196:199], v[20:23]
	v_mfma_f32_16x16x32_f16 v[12:15], v[130:133], v[204:207], v[12:15]
	v_mfma_f32_16x16x32_f16 v[4:7], v[150:153], v[204:207], v[4:7]
	v_mfma_f32_16x16x32_f16 v[60:63], v[146:149], v[184:187], v[60:63]
	v_mfma_f32_16x16x32_f16 v[52:55], v[154:157], v[184:187], v[52:55]
	v_mfma_f32_16x16x32_f16 v[44:47], v[146:149], v[192:195], v[44:47]
	v_mfma_f32_16x16x32_f16 v[36:39], v[154:157], v[192:195], v[36:39]
	v_mfma_f32_16x16x32_f16 v[28:31], v[146:149], v[200:203], v[28:31]
	v_mfma_f32_16x16x32_f16 v[20:23], v[154:157], v[200:203], v[20:23]
	v_mfma_f32_16x16x32_f16 v[12:15], v[146:149], v[216:219], v[12:15]
	v_mfma_f32_16x16x32_f16 v[4:7], v[154:157], v[216:219], v[4:7]
	v_mfma_f32_16x16x32_f16 v[56:59], v[158:161], v[180:183], v[56:59]
	v_mfma_f32_16x16x32_f16 v[48:51], v[168:171], v[180:183], v[48:51]
	v_mfma_f32_16x16x32_f16 v[40:43], v[158:161], v[188:191], v[40:43]
	v_mfma_f32_16x16x32_f16 v[32:35], v[168:171], v[188:191], v[32:35]
	v_mfma_f32_16x16x32_f16 v[24:27], v[158:161], v[196:199], v[24:27]
	v_mfma_f32_16x16x32_f16 v[16:19], v[168:171], v[196:199], v[16:19]
	v_mfma_f32_16x16x32_f16 v[8:11], v[158:161], v[204:207], v[8:11]
	v_mfma_f32_16x16x32_f16 v[0:3], v[168:171], v[204:207], v[0:3]
	v_mfma_f32_16x16x32_f16 v[56:59], v[162:165], v[184:187], v[56:59]
	v_mfma_f32_16x16x32_f16 v[48:51], v[176:179], v[184:187], v[48:51]
	v_mfma_f32_16x16x32_f16 v[40:43], v[162:165], v[192:195], v[40:43]
	v_mfma_f32_16x16x32_f16 v[32:35], v[176:179], v[192:195], v[32:35]
	v_mfma_f32_16x16x32_f16 v[24:27], v[162:165], v[200:203], v[24:27]
	v_mfma_f32_16x16x32_f16 v[16:19], v[176:179], v[200:203], v[16:19]
	v_mfma_f32_16x16x32_f16 v[8:11], v[162:165], v[216:219], v[8:11]
	v_mfma_f32_16x16x32_f16 v[0:3], v[176:179], v[216:219], v[0:3]
	s_setprio 0
	s_barrier
	s_add_i32 s57, s57, 2
	s_add_u32 s22, s22, 0x100
	s_addc_u32 s23, s23, 0
	s_add_u32 s55, s55, 0x100
	s_addc_u32 s56, s56, 0
	s_cmp_gt_u32 s57, 13
	s_cbranch_scc0 .LBB0_68
	s_and_b64 vcc, exec, s[10:11]
	s_cbranch_vccz .LBB0_71
	s_barrier

.LBB0_331:
	s_add_i32 s80, s48, 2
	s_add_u32 s81, s42, 0x80
	s_addc_u32 s49, s43, 0
	s_add_i32 s84, 0, 0x10000
	s_cmp_eq_u32 s74, s48
	s_cselect_b32 s49, s35, s49
	s_cselect_b32 s48, s34, s81
	s_cselect_b32 s87, s37, s57
	s_cselect_b32 s86, s36, s56
	s_add_i32 s81, 0, 0x14000
	v_add_u32_e32 v142, s84, v186
	v_add_u32_e32 v170, s81, v186
	ds_read_b128 v[130:133], v142
	ds_read_b128 v[134:137], v142 offset:1024
	ds_read_b128 v[138:141], v142 offset:2048
	ds_read_b128 v[142:145], v142 offset:3072
	ds_read_b128 v[146:149], v170
	ds_read_b128 v[150:153], v170 offset:1024
	ds_read_b128 v[154:157], v170 offset:2048
	ds_read_b128 v[170:173], v170 offset:3072
	v_lshl_add_u64 v[210:211], s[42:43], 0, v[164:165]
	s_add_i32 m0, s45, 0xc000
	ds_read_b128 v[174:177], v188
	ds_read_b128 v[178:181], v188 offset:1024
	ds_read_b128 v[182:185], v188 offset:2048
	ds_read_b128 v[190:193], v188 offset:3072
	ds_read_b128 v[194:197], v188 offset:4096
	ds_read_b128 v[198:201], v188 offset:5120
	ds_read_b128 v[202:205], v188 offset:6144
	ds_read_b128 v[206:209], v188 offset:7168
	global_load_lds_dwordx4 v[210:211], off
	v_lshl_add_u64 v[210:211], s[42:43], 0, v[168:169]
	s_add_i32 m0, s45, 0xe000
	s_nop 0
	global_load_lds_dwordx4 v[210:211], off
	s_waitcnt vmcnt(8)
	s_waitcnt lgkmcnt(0)
	s_barrier
	s_setprio 1
	s_waitcnt lgkmcnt(0)
	v_mfma_f32_16x16x32_bf16 v[126:129], v[130:133], v[174:177], v[126:129]
	v_mfma_f32_16x16x32_bf16 v[122:125], v[138:141], v[174:177], v[122:125]
	v_mfma_f32_16x16x32_bf16 v[110:113], v[130:133], v[182:185], v[110:113]
	v_mfma_f32_16x16x32_bf16 v[106:109], v[138:141], v[182:185], v[106:109]
	v_mfma_f32_16x16x32_bf16 v[92:95], v[130:133], v[194:197], v[92:95]
	v_mfma_f32_16x16x32_bf16 v[88:91], v[138:141], v[194:197], v[88:91]
	v_mfma_f32_16x16x32_bf16 v[76:79], v[130:133], v[202:205], v[76:79]
	v_mfma_f32_16x16x32_bf16 v[72:75], v[138:141], v[202:205], v[72:75]
	v_mfma_f32_16x16x32_bf16 v[126:129], v[134:137], v[178:181], v[126:129]
	v_mfma_f32_16x16x32_bf16 v[122:125], v[142:145], v[178:181], v[122:125]
	v_mfma_f32_16x16x32_bf16 v[110:113], v[134:137], v[190:193], v[110:113]
	v_mfma_f32_16x16x32_bf16 v[106:109], v[142:145], v[190:193], v[106:109]
	v_mfma_f32_16x16x32_bf16 v[92:95], v[134:137], v[198:201], v[92:95]
	v_mfma_f32_16x16x32_bf16 v[88:91], v[142:145], v[198:201], v[88:91]
	v_mfma_f32_16x16x32_bf16 v[76:79], v[134:137], v[206:209], v[76:79]
	v_mfma_f32_16x16x32_bf16 v[72:75], v[142:145], v[206:209], v[72:75]
	v_mfma_f32_16x16x32_bf16 v[118:121], v[146:149], v[174:177], v[118:121]
	v_mfma_f32_16x16x32_bf16 v[114:117], v[154:157], v[174:177], v[114:117]
	v_mfma_f32_16x16x32_bf16 v[102:105], v[146:149], v[182:185], v[102:105]
	v_mfma_f32_16x16x32_bf16 v[98:101], v[154:157], v[182:185], v[98:101]
	v_mfma_f32_16x16x32_bf16 v[84:87], v[146:149], v[194:197], v[84:87]
	v_mfma_f32_16x16x32_bf16 v[80:83], v[154:157], v[194:197], v[80:83]
	v_mfma_f32_16x16x32_bf16 v[68:71], v[146:149], v[202:205], v[68:71]
	v_mfma_f32_16x16x32_bf16 v[64:67], v[154:157], v[202:205], v[64:67]
	v_mfma_f32_16x16x32_bf16 v[118:121], v[150:153], v[178:181], v[118:121]
	v_mfma_f32_16x16x32_bf16 v[114:117], v[170:173], v[178:181], v[114:117]
	v_mfma_f32_16x16x32_bf16 v[102:105], v[150:153], v[190:193], v[102:105]
	v_mfma_f32_16x16x32_bf16 v[98:101], v[170:173], v[190:193], v[98:101]
	v_mfma_f32_16x16x32_bf16 v[84:87], v[150:153], v[198:201], v[84:87]
	v_mfma_f32_16x16x32_bf16 v[80:83], v[170:173], v[198:201], v[80:83]
	v_mfma_f32_16x16x32_bf16 v[68:71], v[150:153], v[206:209], v[68:71]
	v_mfma_f32_16x16x32_bf16 v[64:67], v[170:173], v[206:209], v[64:67]
	s_setprio 0
	s_barrier
	s_add_i32 s84, s84, s8
	v_lshl_add_u64 v[210:211], s[86:87], 0, v[96:97]
	s_mov_b32 m0, s84
	ds_read_b128 v[174:177], v188 offset:16384
	ds_read_b128 v[178:181], v188 offset:17408
	ds_read_b128 v[182:185], v188 offset:18432
	ds_read_b128 v[190:193], v188 offset:19456
	ds_read_b128 v[194:197], v188 offset:20480
	ds_read_b128 v[198:201], v188 offset:21504
	ds_read_b128 v[202:205], v188 offset:22528
	ds_read_b128 v[206:209], v188 offset:23552
	global_load_lds_dwordx4 v[210:211], off
	s_add_i32 m0, s84, 0x2000
	v_lshl_add_u64 v[212:213], s[86:87], 0, v[162:163]
	s_add_u32 s86, s86, s16
	s_addc_u32 s87, s87, 0
	s_add_i32 s81, s81, s8
	global_load_lds_dwordx4 v[212:213], off
	v_lshl_add_u64 v[216:217], s[86:87], 0, v[96:97]
	s_mov_b32 m0, s81
	v_lshl_add_u64 v[218:219], s[86:87], 0, v[162:163]
	global_load_lds_dwordx4 v[216:217], off
	s_add_i32 m0, s81, 0x2000
	v_lshl_add_u64 v[220:221], s[48:49], 0, v[158:159]
	global_load_lds_dwordx4 v[218:219], off
	s_mov_b32 m0, s45
	v_lshl_add_u64 v[222:223], s[48:49], 0, v[160:161]
	global_load_lds_dwordx4 v[220:221], off
	s_mov_b32 m0, s55
	s_nop 0
	global_load_lds_dwordx4 v[222:223], off
	s_waitcnt vmcnt(8)
	s_waitcnt lgkmcnt(0)
	s_barrier
	s_setprio 1
	s_waitcnt lgkmcnt(0)
	v_mfma_f32_16x16x32_bf16 v[60:63], v[130:133], v[174:177], v[60:63]
	v_mfma_f32_16x16x32_bf16 v[56:59], v[138:141], v[174:177], v[56:59]
	v_mfma_f32_16x16x32_bf16 v[44:47], v[130:133], v[182:185], v[44:47]
	v_mfma_f32_16x16x32_bf16 v[40:43], v[138:141], v[182:185], v[40:43]
	v_mfma_f32_16x16x32_bf16 v[28:31], v[130:133], v[194:197], v[28:31]
	v_mfma_f32_16x16x32_bf16 v[24:27], v[138:141], v[194:197], v[24:27]
	v_mfma_f32_16x16x32_bf16 v[12:15], v[130:133], v[202:205], v[12:15]
	v_mfma_f32_16x16x32_bf16 v[8:11], v[138:141], v[202:205], v[8:11]
	v_mfma_f32_16x16x32_bf16 v[60:63], v[134:137], v[178:181], v[60:63]
	v_mfma_f32_16x16x32_bf16 v[56:59], v[142:145], v[178:181], v[56:59]
	v_mfma_f32_16x16x32_bf16 v[44:47], v[134:137], v[190:193], v[44:47]
	v_mfma_f32_16x16x32_bf16 v[40:43], v[142:145], v[190:193], v[40:43]
	v_mfma_f32_16x16x32_bf16 v[28:31], v[134:137], v[198:201], v[28:31]
	v_mfma_f32_16x16x32_bf16 v[24:27], v[142:145], v[198:201], v[24:27]
	v_mfma_f32_16x16x32_bf16 v[12:15], v[134:137], v[206:209], v[12:15]
	v_mfma_f32_16x16x32_bf16 v[8:11], v[142:145], v[206:209], v[8:11]
	v_mfma_f32_16x16x32_bf16 v[52:55], v[146:149], v[174:177], v[52:55]
	v_mfma_f32_16x16x32_bf16 v[48:51], v[154:157], v[174:177], v[48:51]
	v_mfma_f32_16x16x32_bf16 v[36:39], v[146:149], v[182:185], v[36:39]
	v_mfma_f32_16x16x32_bf16 v[32:35], v[154:157], v[182:185], v[32:35]
	v_mfma_f32_16x16x32_bf16 v[20:23], v[146:149], v[194:197], v[20:23]
	v_mfma_f32_16x16x32_bf16 v[16:19], v[154:157], v[194:197], v[16:19]
	v_mfma_f32_16x16x32_bf16 v[4:7], v[146:149], v[202:205], v[4:7]
	v_mfma_f32_16x16x32_bf16 v[0:3], v[154:157], v[202:205], v[0:3]
	v_mfma_f32_16x16x32_bf16 v[52:55], v[150:153], v[178:181], v[52:55]
	v_mfma_f32_16x16x32_bf16 v[48:51], v[170:173], v[178:181], v[48:51]
	v_mfma_f32_16x16x32_bf16 v[36:39], v[150:153], v[190:193], v[36:39]
	v_mfma_f32_16x16x32_bf16 v[32:35], v[170:173], v[190:193], v[32:35]
	v_mfma_f32_16x16x32_bf16 v[20:23], v[150:153], v[198:201], v[20:23]
	v_mfma_f32_16x16x32_bf16 v[16:19], v[170:173], v[198:201], v[16:19]
	v_mfma_f32_16x16x32_bf16 v[4:7], v[150:153], v[206:209], v[4:7]
	v_mfma_f32_16x16x32_bf16 v[0:3], v[170:173], v[206:209], v[0:3]
	s_setprio 0
	s_barrier
	s_add_i32 s81, 0, 0x18000
	s_add_i32 s84, 0, 0x1c000
	v_add_u32_e32 v142, s81, v186
	v_add_u32_e32 v170, s84, v186
	ds_read_b128 v[130:133], v142
	ds_read_b128 v[134:137], v142 offset:1024
	ds_read_b128 v[138:141], v142 offset:2048
	ds_read_b128 v[142:145], v142 offset:3072
	ds_read_b128 v[146:149], v170
	ds_read_b128 v[150:153], v170 offset:1024
	ds_read_b128 v[154:157], v170 offset:2048
	ds_read_b128 v[170:173], v170 offset:3072
	s_add_u32 s48, s48, s16
	s_addc_u32 s49, s49, 0
	s_mov_b32 m0, s60
	v_lshl_add_u64 v[224:225], s[48:49], 0, v[158:159]
	ds_read_b128 v[174:177], v188 offset:32768
	ds_read_b128 v[178:181], v188 offset:33792
	ds_read_b128 v[182:185], v188 offset:34816
	ds_read_b128 v[190:193], v188 offset:35840
	ds_read_b128 v[194:197], v188 offset:36864
	ds_read_b128 v[198:201], v188 offset:37888
	ds_read_b128 v[202:205], v188 offset:38912
	ds_read_b128 v[206:209], v188 offset:39936
	global_load_lds_dwordx4 v[224:225], off
	v_lshl_add_u64 v[224:225], s[48:49], 0, v[160:161]
	s_mov_b32 m0, s61
	s_nop 0
	global_load_lds_dwordx4 v[224:225], off
	s_waitcnt vmcnt(8)
	s_waitcnt lgkmcnt(0)
	s_barrier
	s_setprio 1
	s_waitcnt lgkmcnt(0)
	v_mfma_f32_16x16x32_bf16 v[126:129], v[130:133], v[174:177], v[126:129]
	v_mfma_f32_16x16x32_bf16 v[122:125], v[138:141], v[174:177], v[122:125]
	v_mfma_f32_16x16x32_bf16 v[110:113], v[130:133], v[182:185], v[110:113]
	v_mfma_f32_16x16x32_bf16 v[106:109], v[138:141], v[182:185], v[106:109]
	v_mfma_f32_16x16x32_bf16 v[92:95], v[130:133], v[194:197], v[92:95]
	v_mfma_f32_16x16x32_bf16 v[88:91], v[138:141], v[194:197], v[88:91]
	v_mfma_f32_16x16x32_bf16 v[76:79], v[130:133], v[202:205], v[76:79]
	v_mfma_f32_16x16x32_bf16 v[72:75], v[138:141], v[202:205], v[72:75]
	v_mfma_f32_16x16x32_bf16 v[126:129], v[134:137], v[178:181], v[126:129]
	v_mfma_f32_16x16x32_bf16 v[122:125], v[142:145], v[178:181], v[122:125]
	v_mfma_f32_16x16x32_bf16 v[110:113], v[134:137], v[190:193], v[110:113]
	v_mfma_f32_16x16x32_bf16 v[106:109], v[142:145], v[190:193], v[106:109]
	v_mfma_f32_16x16x32_bf16 v[92:95], v[134:137], v[198:201], v[92:95]
	v_mfma_f32_16x16x32_bf16 v[88:91], v[142:145], v[198:201], v[88:91]
	v_mfma_f32_16x16x32_bf16 v[76:79], v[134:137], v[206:209], v[76:79]
	v_mfma_f32_16x16x32_bf16 v[72:75], v[142:145], v[206:209], v[72:75]
	v_mfma_f32_16x16x32_bf16 v[118:121], v[146:149], v[174:177], v[118:121]
	v_mfma_f32_16x16x32_bf16 v[114:117], v[154:157], v[174:177], v[114:117]
	v_mfma_f32_16x16x32_bf16 v[102:105], v[146:149], v[182:185], v[102:105]
	v_mfma_f32_16x16x32_bf16 v[98:101], v[154:157], v[182:185], v[98:101]
	v_mfma_f32_16x16x32_bf16 v[84:87], v[146:149], v[194:197], v[84:87]
	v_mfma_f32_16x16x32_bf16 v[80:83], v[154:157], v[194:197], v[80:83]
	v_mfma_f32_16x16x32_bf16 v[68:71], v[146:149], v[202:205], v[68:71]
	v_mfma_f32_16x16x32_bf16 v[64:67], v[154:157], v[202:205], v[64:67]
	v_mfma_f32_16x16x32_bf16 v[118:121], v[150:153], v[178:181], v[118:121]
	v_mfma_f32_16x16x32_bf16 v[114:117], v[170:173], v[178:181], v[114:117]
	v_mfma_f32_16x16x32_bf16 v[102:105], v[150:153], v[190:193], v[102:105]
	v_mfma_f32_16x16x32_bf16 v[98:101], v[170:173], v[190:193], v[98:101]
	v_mfma_f32_16x16x32_bf16 v[84:87], v[150:153], v[198:201], v[84:87]
	v_mfma_f32_16x16x32_bf16 v[80:83], v[170:173], v[198:201], v[80:83]
	v_mfma_f32_16x16x32_bf16 v[68:71], v[150:153], v[206:209], v[68:71]
	v_mfma_f32_16x16x32_bf16 v[64:67], v[170:173], v[206:209], v[64:67]
	s_setprio 0
	s_barrier
	s_add_i32 s48, s81, s8
	v_lshl_add_u64 v[210:211], v[210:211], 0, s[94:95]
	s_mov_b32 m0, s48
	ds_read_b128 v[174:177], v188 offset:49152
	ds_read_b128 v[178:181], v188 offset:50176
	ds_read_b128 v[182:185], v188 offset:51200
	ds_read_b128 v[190:193], v188 offset:52224
	ds_read_b128 v[194:197], v188 offset:53248
	ds_read_b128 v[198:201], v188 offset:54272
	ds_read_b128 v[202:205], v188 offset:55296
	ds_read_b128 v[206:209], v188 offset:56320
	global_load_lds_dwordx4 v[210:211], off
	v_lshl_add_u64 v[210:211], v[212:213], 0, s[94:95]
	s_add_i32 m0, s48, 0x2000
	s_add_i32 s48, s84, s8
	global_load_lds_dwordx4 v[210:211], off
	v_lshl_add_u64 v[210:211], v[216:217], 0, s[94:95]
	s_mov_b32 m0, s48
	s_nop 0
	global_load_lds_dwordx4 v[210:211], off
	v_lshl_add_u64 v[210:211], v[218:219], 0, s[94:95]
	s_add_i32 m0, s48, 0x2000
	s_nop 0
	global_load_lds_dwordx4 v[210:211], off
	v_lshl_add_u64 v[210:211], v[220:221], 0, s[94:95]
	s_mov_b32 m0, s70
	s_nop 0
	global_load_lds_dwordx4 v[210:211], off
	v_lshl_add_u64 v[210:211], v[222:223], 0, s[94:95]
	s_mov_b32 m0, s73
	s_nop 0
	global_load_lds_dwordx4 v[210:211], off
	s_waitcnt vmcnt(8)
	s_waitcnt lgkmcnt(0)
	s_barrier
	s_setprio 1
	s_waitcnt lgkmcnt(0)
	v_mfma_f32_16x16x32_bf16 v[60:63], v[130:133], v[174:177], v[60:63]
	v_mfma_f32_16x16x32_bf16 v[56:59], v[138:141], v[174:177], v[56:59]
	v_mfma_f32_16x16x32_bf16 v[44:47], v[130:133], v[182:185], v[44:47]
	v_mfma_f32_16x16x32_bf16 v[40:43], v[138:141], v[182:185], v[40:43]
	v_mfma_f32_16x16x32_bf16 v[28:31], v[130:133], v[194:197], v[28:31]
	v_mfma_f32_16x16x32_bf16 v[24:27], v[138:141], v[194:197], v[24:27]
	v_mfma_f32_16x16x32_bf16 v[12:15], v[130:133], v[202:205], v[12:15]
	v_mfma_f32_16x16x32_bf16 v[8:11], v[138:141], v[202:205], v[8:11]
	v_mfma_f32_16x16x32_bf16 v[60:63], v[134:137], v[178:181], v[60:63]
	v_mfma_f32_16x16x32_bf16 v[56:59], v[142:145], v[178:181], v[56:59]
	v_mfma_f32_16x16x32_bf16 v[44:47], v[134:137], v[190:193], v[44:47]
	v_mfma_f32_16x16x32_bf16 v[40:43], v[142:145], v[190:193], v[40:43]
	v_mfma_f32_16x16x32_bf16 v[28:31], v[134:137], v[198:201], v[28:31]
	v_mfma_f32_16x16x32_bf16 v[24:27], v[142:145], v[198:201], v[24:27]
	v_mfma_f32_16x16x32_bf16 v[12:15], v[134:137], v[206:209], v[12:15]
	v_mfma_f32_16x16x32_bf16 v[8:11], v[142:145], v[206:209], v[8:11]
	v_mfma_f32_16x16x32_bf16 v[52:55], v[146:149], v[174:177], v[52:55]
	v_mfma_f32_16x16x32_bf16 v[48:51], v[154:157], v[174:177], v[48:51]
	v_mfma_f32_16x16x32_bf16 v[36:39], v[146:149], v[182:185], v[36:39]
	v_mfma_f32_16x16x32_bf16 v[32:35], v[154:157], v[182:185], v[32:35]
	v_mfma_f32_16x16x32_bf16 v[20:23], v[146:149], v[194:197], v[20:23]
	v_mfma_f32_16x16x32_bf16 v[16:19], v[154:157], v[194:197], v[16:19]
	v_mfma_f32_16x16x32_bf16 v[4:7], v[146:149], v[202:205], v[4:7]
	v_mfma_f32_16x16x32_bf16 v[0:3], v[154:157], v[202:205], v[0:3]
	v_mfma_f32_16x16x32_bf16 v[52:55], v[150:153], v[178:181], v[52:55]
	v_mfma_f32_16x16x32_bf16 v[48:51], v[170:173], v[178:181], v[48:51]
	v_mfma_f32_16x16x32_bf16 v[36:39], v[150:153], v[190:193], v[36:39]
	v_mfma_f32_16x16x32_bf16 v[32:35], v[170:173], v[190:193], v[32:35]
	v_mfma_f32_16x16x32_bf16 v[20:23], v[150:153], v[198:201], v[20:23]
	v_mfma_f32_16x16x32_bf16 v[16:19], v[170:173], v[198:201], v[16:19]
	v_mfma_f32_16x16x32_bf16 v[4:7], v[150:153], v[206:209], v[4:7]
	v_mfma_f32_16x16x32_bf16 v[0:3], v[170:173], v[206:209], v[0:3]
	s_setprio 0
	s_barrier
	s_add_u32 s42, s42, 0x100
	s_addc_u32 s43, s43, 0
	s_add_u32 s56, s56, 0x100
	s_addc_u32 s57, s57, 0
	s_cmp_ge_u32 s80, s69
	s_mov_b32 s48, s80
	s_cbranch_scc0 .LBB0_331
	s_and_b64 vcc, exec, s[28:29]
	s_cbranch_vccz .LBB0_334
	s_barrier

.LBB0_511:
	s_add_i32 s84, s46, 2
	s_add_u32 s86, s36, 0x80
	s_addc_u32 s47, s37, 0
	s_add_i32 vcc_lo, 0, 0x10000
	s_cmp_eq_u32 s33, s46
	s_cselect_b32 s47, s31, s47
	s_cselect_b32 s46, s30, s86
	s_cselect_b32 s87, s35, s49
	s_cselect_b32 s86, s34, s48
	s_add_i32 vcc_hi, 0, 0x14000
	v_add_u32_e32 v154, vcc_lo, v174
	v_add_u32_e32 v172, vcc_hi, v174
	ds_read_b128 v[142:145], v154
	ds_read_b128 v[146:149], v154 offset:1024
	ds_read_b128 v[150:153], v154 offset:2048
	ds_read_b128 v[154:157], v154 offset:3072
	ds_read_b128 v[158:161], v172
	ds_read_b128 v[162:165], v172 offset:1024
	ds_read_b128 v[168:171], v172 offset:2048
	ds_read_b128 v[178:181], v172 offset:3072
	v_lshl_add_u64 v[172:173], s[36:37], 0, v[138:139]
	s_add_i32 m0, s75, 0xc000
	ds_read_b128 v[182:185], v177
	ds_read_b128 v[186:189], v177 offset:1024
	ds_read_b128 v[190:193], v177 offset:2048
	ds_read_b128 v[194:197], v177 offset:3072
	ds_read_b128 v[198:201], v177 offset:4096
	ds_read_b128 v[202:205], v177 offset:5120
	ds_read_b128 v[206:209], v177 offset:6144
	ds_read_b128 v[216:219], v177 offset:7168
	global_load_lds_dwordx4 v[172:173], off
	v_lshl_add_u64 v[172:173], s[36:37], 0, v[140:141]
	s_add_i32 m0, s75, 0xe000
	s_nop 0
	global_load_lds_dwordx4 v[172:173], off
	s_waitcnt vmcnt(8)
	s_waitcnt lgkmcnt(0)
	s_barrier
	s_setprio 1
	s_waitcnt lgkmcnt(0)
	v_mfma_f32_16x16x32_bf16 v[126:129], v[142:145], v[182:185], v[126:129]
	v_mfma_f32_16x16x32_bf16 v[122:125], v[150:153], v[182:185], v[122:125]
	v_mfma_f32_16x16x32_bf16 v[110:113], v[142:145], v[190:193], v[110:113]
	v_mfma_f32_16x16x32_bf16 v[106:109], v[150:153], v[190:193], v[106:109]
	v_mfma_f32_16x16x32_bf16 v[92:95], v[142:145], v[198:201], v[92:95]
	v_mfma_f32_16x16x32_bf16 v[88:91], v[150:153], v[198:201], v[88:91]
	v_mfma_f32_16x16x32_bf16 v[76:79], v[142:145], v[206:209], v[76:79]
	v_mfma_f32_16x16x32_bf16 v[72:75], v[150:153], v[206:209], v[72:75]
	v_mfma_f32_16x16x32_bf16 v[126:129], v[146:149], v[186:189], v[126:129]
	v_mfma_f32_16x16x32_bf16 v[122:125], v[154:157], v[186:189], v[122:125]
	v_mfma_f32_16x16x32_bf16 v[110:113], v[146:149], v[194:197], v[110:113]
	v_mfma_f32_16x16x32_bf16 v[106:109], v[154:157], v[194:197], v[106:109]
	v_mfma_f32_16x16x32_bf16 v[92:95], v[146:149], v[202:205], v[92:95]
	v_mfma_f32_16x16x32_bf16 v[88:91], v[154:157], v[202:205], v[88:91]
	v_mfma_f32_16x16x32_bf16 v[76:79], v[146:149], v[216:219], v[76:79]
	v_mfma_f32_16x16x32_bf16 v[72:75], v[154:157], v[216:219], v[72:75]
	v_mfma_f32_16x16x32_bf16 v[118:121], v[158:161], v[182:185], v[118:121]
	v_mfma_f32_16x16x32_bf16 v[114:117], v[168:171], v[182:185], v[114:117]
	v_mfma_f32_16x16x32_bf16 v[102:105], v[158:161], v[190:193], v[102:105]
	v_mfma_f32_16x16x32_bf16 v[98:101], v[168:171], v[190:193], v[98:101]
	v_mfma_f32_16x16x32_bf16 v[84:87], v[158:161], v[198:201], v[84:87]
	v_mfma_f32_16x16x32_bf16 v[80:83], v[168:171], v[198:201], v[80:83]
	v_mfma_f32_16x16x32_bf16 v[68:71], v[158:161], v[206:209], v[68:71]
	v_mfma_f32_16x16x32_bf16 v[64:67], v[168:171], v[206:209], v[64:67]
	v_mfma_f32_16x16x32_bf16 v[118:121], v[162:165], v[186:189], v[118:121]
	v_mfma_f32_16x16x32_bf16 v[114:117], v[178:181], v[186:189], v[114:117]
	v_mfma_f32_16x16x32_bf16 v[102:105], v[162:165], v[194:197], v[102:105]
	v_mfma_f32_16x16x32_bf16 v[98:101], v[178:181], v[194:197], v[98:101]
	v_mfma_f32_16x16x32_bf16 v[84:87], v[162:165], v[202:205], v[84:87]
	v_mfma_f32_16x16x32_bf16 v[80:83], v[178:181], v[202:205], v[80:83]
	v_mfma_f32_16x16x32_bf16 v[68:71], v[162:165], v[216:219], v[68:71]
	v_mfma_f32_16x16x32_bf16 v[64:67], v[178:181], v[216:219], v[64:67]
	s_setprio 0
	s_barrier
	s_add_i32 vcc_lo, vcc_lo, s71
	v_lshl_add_u64 v[172:173], s[86:87], 0, v[96:97]
	s_mov_b32 m0, vcc_lo
	ds_read_b128 v[182:185], v177 offset:16384
	ds_read_b128 v[186:189], v177 offset:17408
	ds_read_b128 v[190:193], v177 offset:18432
	ds_read_b128 v[194:197], v177 offset:19456
	ds_read_b128 v[198:201], v177 offset:20480
	ds_read_b128 v[202:205], v177 offset:21504
	ds_read_b128 v[206:209], v177 offset:22528
	ds_read_b128 v[216:219], v177 offset:23552
	global_load_lds_dwordx4 v[172:173], off
	s_add_i32 m0, vcc_lo, 0x2000
	v_lshl_add_u64 v[210:211], s[86:87], 0, v[134:135]
	s_add_u32 s86, s86, s8
	s_addc_u32 s87, s87, 0
	s_add_i32 vcc_lo, vcc_hi, s71
	global_load_lds_dwordx4 v[210:211], off
	v_lshl_add_u64 v[212:213], s[86:87], 0, v[96:97]
	s_mov_b32 m0, vcc_lo
	v_lshl_add_u64 v[220:221], s[86:87], 0, v[134:135]
	global_load_lds_dwordx4 v[212:213], off
	s_add_i32 m0, vcc_lo, 0x2000
	v_lshl_add_u64 v[222:223], s[46:47], 0, v[130:131]
	global_load_lds_dwordx4 v[220:221], off
	s_mov_b32 m0, s75
	v_lshl_add_u64 v[224:225], s[46:47], 0, v[132:133]
	global_load_lds_dwordx4 v[222:223], off
	s_mov_b32 m0, s76
	s_nop 0
	global_load_lds_dwordx4 v[224:225], off
	s_waitcnt vmcnt(8)
	s_waitcnt lgkmcnt(0)
	s_barrier
	s_setprio 1
	s_waitcnt lgkmcnt(0)
	v_mfma_f32_16x16x32_bf16 v[60:63], v[142:145], v[182:185], v[60:63]
	v_mfma_f32_16x16x32_bf16 v[56:59], v[150:153], v[182:185], v[56:59]
	v_mfma_f32_16x16x32_bf16 v[44:47], v[142:145], v[190:193], v[44:47]
	v_mfma_f32_16x16x32_bf16 v[40:43], v[150:153], v[190:193], v[40:43]
	v_mfma_f32_16x16x32_bf16 v[28:31], v[142:145], v[198:201], v[28:31]
	v_mfma_f32_16x16x32_bf16 v[24:27], v[150:153], v[198:201], v[24:27]
	v_mfma_f32_16x16x32_bf16 v[12:15], v[142:145], v[206:209], v[12:15]
	v_mfma_f32_16x16x32_bf16 v[8:11], v[150:153], v[206:209], v[8:11]
	v_mfma_f32_16x16x32_bf16 v[60:63], v[146:149], v[186:189], v[60:63]
	v_mfma_f32_16x16x32_bf16 v[56:59], v[154:157], v[186:189], v[56:59]
	v_mfma_f32_16x16x32_bf16 v[44:47], v[146:149], v[194:197], v[44:47]
	v_mfma_f32_16x16x32_bf16 v[40:43], v[154:157], v[194:197], v[40:43]
	v_mfma_f32_16x16x32_bf16 v[28:31], v[146:149], v[202:205], v[28:31]
	v_mfma_f32_16x16x32_bf16 v[24:27], v[154:157], v[202:205], v[24:27]
	v_mfma_f32_16x16x32_bf16 v[12:15], v[146:149], v[216:219], v[12:15]
	v_mfma_f32_16x16x32_bf16 v[8:11], v[154:157], v[216:219], v[8:11]
	v_mfma_f32_16x16x32_bf16 v[52:55], v[158:161], v[182:185], v[52:55]
	v_mfma_f32_16x16x32_bf16 v[48:51], v[168:171], v[182:185], v[48:51]
	v_mfma_f32_16x16x32_bf16 v[36:39], v[158:161], v[190:193], v[36:39]
	v_mfma_f32_16x16x32_bf16 v[32:35], v[168:171], v[190:193], v[32:35]
	v_mfma_f32_16x16x32_bf16 v[20:23], v[158:161], v[198:201], v[20:23]
	v_mfma_f32_16x16x32_bf16 v[16:19], v[168:171], v[198:201], v[16:19]
	v_mfma_f32_16x16x32_bf16 v[4:7], v[158:161], v[206:209], v[4:7]
	v_mfma_f32_16x16x32_bf16 v[0:3], v[168:171], v[206:209], v[0:3]
	v_mfma_f32_16x16x32_bf16 v[52:55], v[162:165], v[186:189], v[52:55]
	v_mfma_f32_16x16x32_bf16 v[48:51], v[178:181], v[186:189], v[48:51]
	v_mfma_f32_16x16x32_bf16 v[36:39], v[162:165], v[194:197], v[36:39]
	v_mfma_f32_16x16x32_bf16 v[32:35], v[178:181], v[194:197], v[32:35]
	v_mfma_f32_16x16x32_bf16 v[20:23], v[162:165], v[202:205], v[20:23]
	v_mfma_f32_16x16x32_bf16 v[16:19], v[178:181], v[202:205], v[16:19]
	v_mfma_f32_16x16x32_bf16 v[4:7], v[162:165], v[216:219], v[4:7]
	v_mfma_f32_16x16x32_bf16 v[0:3], v[178:181], v[216:219], v[0:3]
	s_setprio 0
	s_barrier
	s_add_i32 s86, 0, 0x18000
	s_add_i32 s87, 0, 0x1c000
	v_add_u32_e32 v154, s86, v174
	v_add_u32_e32 v178, s87, v174
	ds_read_b128 v[142:145], v154
	ds_read_b128 v[146:149], v154 offset:1024
	ds_read_b128 v[150:153], v154 offset:2048
	ds_read_b128 v[154:157], v154 offset:3072
	ds_read_b128 v[158:161], v178
	ds_read_b128 v[162:165], v178 offset:1024
	ds_read_b128 v[168:171], v178 offset:2048
	ds_read_b128 v[178:181], v178 offset:3072
	s_add_u32 s46, s46, s20
	s_addc_u32 s47, s47, 0
	s_mov_b32 m0, s77
	v_lshl_add_u64 v[226:227], s[46:47], 0, v[130:131]
	ds_read_b128 v[182:185], v177 offset:32768
	ds_read_b128 v[186:189], v177 offset:33792
	ds_read_b128 v[190:193], v177 offset:34816
	ds_read_b128 v[194:197], v177 offset:35840
	ds_read_b128 v[198:201], v177 offset:36864
	ds_read_b128 v[202:205], v177 offset:37888
	ds_read_b128 v[206:209], v177 offset:38912
	ds_read_b128 v[216:219], v177 offset:39936
	global_load_lds_dwordx4 v[226:227], off
	v_lshl_add_u64 v[226:227], s[46:47], 0, v[132:133]
	s_mov_b32 m0, s78
	s_nop 0
	global_load_lds_dwordx4 v[226:227], off
	s_waitcnt vmcnt(8)
	s_waitcnt lgkmcnt(0)
	s_barrier
	s_setprio 1
	s_waitcnt lgkmcnt(0)
	v_mfma_f32_16x16x32_bf16 v[126:129], v[142:145], v[182:185], v[126:129]
	v_mfma_f32_16x16x32_bf16 v[122:125], v[150:153], v[182:185], v[122:125]
	v_mfma_f32_16x16x32_bf16 v[110:113], v[142:145], v[190:193], v[110:113]
	v_mfma_f32_16x16x32_bf16 v[106:109], v[150:153], v[190:193], v[106:109]
	v_mfma_f32_16x16x32_bf16 v[92:95], v[142:145], v[198:201], v[92:95]
	v_mfma_f32_16x16x32_bf16 v[88:91], v[150:153], v[198:201], v[88:91]
	v_mfma_f32_16x16x32_bf16 v[76:79], v[142:145], v[206:209], v[76:79]
	v_mfma_f32_16x16x32_bf16 v[72:75], v[150:153], v[206:209], v[72:75]
	v_mfma_f32_16x16x32_bf16 v[126:129], v[146:149], v[186:189], v[126:129]
	v_mfma_f32_16x16x32_bf16 v[122:125], v[154:157], v[186:189], v[122:125]
	v_mfma_f32_16x16x32_bf16 v[110:113], v[146:149], v[194:197], v[110:113]
	v_mfma_f32_16x16x32_bf16 v[106:109], v[154:157], v[194:197], v[106:109]
	v_mfma_f32_16x16x32_bf16 v[92:95], v[146:149], v[202:205], v[92:95]
	v_mfma_f32_16x16x32_bf16 v[88:91], v[154:157], v[202:205], v[88:91]
	v_mfma_f32_16x16x32_bf16 v[76:79], v[146:149], v[216:219], v[76:79]
	v_mfma_f32_16x16x32_bf16 v[72:75], v[154:157], v[216:219], v[72:75]
	v_mfma_f32_16x16x32_bf16 v[118:121], v[158:161], v[182:185], v[118:121]
	v_mfma_f32_16x16x32_bf16 v[114:117], v[168:171], v[182:185], v[114:117]
	v_mfma_f32_16x16x32_bf16 v[102:105], v[158:161], v[190:193], v[102:105]
	v_mfma_f32_16x16x32_bf16 v[98:101], v[168:171], v[190:193], v[98:101]
	v_mfma_f32_16x16x32_bf16 v[84:87], v[158:161], v[198:201], v[84:87]
	v_mfma_f32_16x16x32_bf16 v[80:83], v[168:171], v[198:201], v[80:83]
	v_mfma_f32_16x16x32_bf16 v[68:71], v[158:161], v[206:209], v[68:71]
	v_mfma_f32_16x16x32_bf16 v[64:67], v[168:171], v[206:209], v[64:67]
	v_mfma_f32_16x16x32_bf16 v[118:121], v[162:165], v[186:189], v[118:121]
	v_mfma_f32_16x16x32_bf16 v[114:117], v[178:181], v[186:189], v[114:117]
	v_mfma_f32_16x16x32_bf16 v[102:105], v[162:165], v[194:197], v[102:105]
	v_mfma_f32_16x16x32_bf16 v[98:101], v[178:181], v[194:197], v[98:101]
	v_mfma_f32_16x16x32_bf16 v[84:87], v[162:165], v[202:205], v[84:87]
	v_mfma_f32_16x16x32_bf16 v[80:83], v[178:181], v[202:205], v[80:83]
	v_mfma_f32_16x16x32_bf16 v[68:71], v[162:165], v[216:219], v[68:71]
	v_mfma_f32_16x16x32_bf16 v[64:67], v[178:181], v[216:219], v[64:67]
	s_setprio 0
	s_barrier
	s_add_i32 s46, s86, s71
	v_lshl_add_u64 v[172:173], v[172:173], 0, s[94:95]
	s_mov_b32 m0, s46
	ds_read_b128 v[182:185], v177 offset:49152
	ds_read_b128 v[186:189], v177 offset:50176
	ds_read_b128 v[190:193], v177 offset:51200
	ds_read_b128 v[194:197], v177 offset:52224
	ds_read_b128 v[198:201], v177 offset:53248
	ds_read_b128 v[202:205], v177 offset:54272
	ds_read_b128 v[206:209], v177 offset:55296
	ds_read_b128 v[216:219], v177 offset:56320
	global_load_lds_dwordx4 v[172:173], off
	v_lshl_add_u64 v[172:173], v[210:211], 0, s[94:95]
	s_add_i32 m0, s46, 0x2000
	s_add_i32 s46, s87, s71
	global_load_lds_dwordx4 v[172:173], off
	v_lshl_add_u64 v[172:173], v[212:213], 0, s[94:95]
	s_mov_b32 m0, s46
	s_nop 0
	global_load_lds_dwordx4 v[172:173], off
	v_lshl_add_u64 v[172:173], v[220:221], 0, s[94:95]
	s_add_i32 m0, s46, 0x2000
	s_nop 0
	global_load_lds_dwordx4 v[172:173], off
	v_lshl_add_u64 v[172:173], v[222:223], 0, s[94:95]
	s_mov_b32 m0, s79
	s_nop 0
	global_load_lds_dwordx4 v[172:173], off
	v_lshl_add_u64 v[172:173], v[224:225], 0, s[94:95]
	s_mov_b32 m0, s80
	s_nop 0
	global_load_lds_dwordx4 v[172:173], off
	s_waitcnt vmcnt(8)
	s_waitcnt lgkmcnt(0)
	s_barrier
	s_setprio 1
	s_waitcnt lgkmcnt(0)
	v_mfma_f32_16x16x32_bf16 v[60:63], v[142:145], v[182:185], v[60:63]
	v_mfma_f32_16x16x32_bf16 v[56:59], v[150:153], v[182:185], v[56:59]
	v_mfma_f32_16x16x32_bf16 v[44:47], v[142:145], v[190:193], v[44:47]
	v_mfma_f32_16x16x32_bf16 v[40:43], v[150:153], v[190:193], v[40:43]
	v_mfma_f32_16x16x32_bf16 v[28:31], v[142:145], v[198:201], v[28:31]
	v_mfma_f32_16x16x32_bf16 v[24:27], v[150:153], v[198:201], v[24:27]
	v_mfma_f32_16x16x32_bf16 v[12:15], v[142:145], v[206:209], v[12:15]
	v_mfma_f32_16x16x32_bf16 v[8:11], v[150:153], v[206:209], v[8:11]
	v_mfma_f32_16x16x32_bf16 v[60:63], v[146:149], v[186:189], v[60:63]
	v_mfma_f32_16x16x32_bf16 v[56:59], v[154:157], v[186:189], v[56:59]
	v_mfma_f32_16x16x32_bf16 v[44:47], v[146:149], v[194:197], v[44:47]
	v_mfma_f32_16x16x32_bf16 v[40:43], v[154:157], v[194:197], v[40:43]
	v_mfma_f32_16x16x32_bf16 v[28:31], v[146:149], v[202:205], v[28:31]
	v_mfma_f32_16x16x32_bf16 v[24:27], v[154:157], v[202:205], v[24:27]
	v_mfma_f32_16x16x32_bf16 v[12:15], v[146:149], v[216:219], v[12:15]
	v_mfma_f32_16x16x32_bf16 v[8:11], v[154:157], v[216:219], v[8:11]
	v_mfma_f32_16x16x32_bf16 v[52:55], v[158:161], v[182:185], v[52:55]
	v_mfma_f32_16x16x32_bf16 v[48:51], v[168:171], v[182:185], v[48:51]
	v_mfma_f32_16x16x32_bf16 v[36:39], v[158:161], v[190:193], v[36:39]
	v_mfma_f32_16x16x32_bf16 v[32:35], v[168:171], v[190:193], v[32:35]
	v_mfma_f32_16x16x32_bf16 v[20:23], v[158:161], v[198:201], v[20:23]
	v_mfma_f32_16x16x32_bf16 v[16:19], v[168:171], v[198:201], v[16:19]
	v_mfma_f32_16x16x32_bf16 v[4:7], v[158:161], v[206:209], v[4:7]
	v_mfma_f32_16x16x32_bf16 v[0:3], v[168:171], v[206:209], v[0:3]
	v_mfma_f32_16x16x32_bf16 v[52:55], v[162:165], v[186:189], v[52:55]
	v_mfma_f32_16x16x32_bf16 v[48:51], v[178:181], v[186:189], v[48:51]
	v_mfma_f32_16x16x32_bf16 v[36:39], v[162:165], v[194:197], v[36:39]
	v_mfma_f32_16x16x32_bf16 v[32:35], v[178:181], v[194:197], v[32:35]
	v_mfma_f32_16x16x32_bf16 v[20:23], v[162:165], v[202:205], v[20:23]
	v_mfma_f32_16x16x32_bf16 v[16:19], v[178:181], v[202:205], v[16:19]
	v_mfma_f32_16x16x32_bf16 v[4:7], v[162:165], v[216:219], v[4:7]
	v_mfma_f32_16x16x32_bf16 v[0:3], v[178:181], v[216:219], v[0:3]
	s_setprio 0
	s_barrier
	s_add_u32 s36, s36, 0x100
	s_addc_u32 s37, s37, 0
	s_add_u32 s48, s48, 0x100
	s_addc_u32 s49, s49, 0
	s_cmp_ge_u32 s84, s2
	s_mov_b32 s46, s84
	s_cbranch_scc0 .LBB0_511
	s_and_b64 vcc, exec, s[26:27]
	s_cbranch_vccz .LBB0_514
	s_barrier

.LBB0_654:
	s_add_i32 s56, s36, 2
	s_add_u32 s57, s34, 0x80
	s_addc_u32 s37, s35, 0
	s_add_i32 s84, 0, 0x10000
	s_cmp_eq_u32 s2, s36
	s_cselect_b32 s37, s9, s37
	s_cselect_b32 s36, s8, s57
	s_cselect_b32 vcc_hi, s31, s47
	s_cselect_b32 vcc_lo, s30, s46
	s_add_i32 s57, 0, 0x14000
	v_add_u32_e32 v154, s84, v174
	v_add_u32_e32 v172, s57, v174
	ds_read_b128 v[142:145], v154
	ds_read_b128 v[146:149], v154 offset:1024
	ds_read_b128 v[150:153], v154 offset:2048
	ds_read_b128 v[154:157], v154 offset:3072
	ds_read_b128 v[158:161], v172
	ds_read_b128 v[162:165], v172 offset:1024
	ds_read_b128 v[168:171], v172 offset:2048
	ds_read_b128 v[178:181], v172 offset:3072
	v_lshl_add_u64 v[172:173], s[34:35], 0, v[138:139]
	s_add_i32 m0, s77, 0xc000
	ds_read_b128 v[182:185], v177
	ds_read_b128 v[186:189], v177 offset:1024
	ds_read_b128 v[190:193], v177 offset:2048
	ds_read_b128 v[194:197], v177 offset:3072
	ds_read_b128 v[198:201], v177 offset:4096
	ds_read_b128 v[202:205], v177 offset:5120
	ds_read_b128 v[206:209], v177 offset:6144
	ds_read_b128 v[216:219], v177 offset:7168
	global_load_lds_dwordx4 v[172:173], off
	v_lshl_add_u64 v[172:173], s[34:35], 0, v[140:141]
	s_add_i32 m0, s77, 0xe000
	s_nop 0
	global_load_lds_dwordx4 v[172:173], off
	s_waitcnt vmcnt(8)
	s_waitcnt lgkmcnt(0)
	s_barrier
	s_setprio 1
	s_waitcnt lgkmcnt(0)
	v_mfma_f32_16x16x32_f16 v[126:129], v[142:145], v[182:185], v[126:129]
	v_mfma_f32_16x16x32_f16 v[122:125], v[150:153], v[182:185], v[122:125]
	v_mfma_f32_16x16x32_f16 v[110:113], v[142:145], v[190:193], v[110:113]
	v_mfma_f32_16x16x32_f16 v[106:109], v[150:153], v[190:193], v[106:109]
	v_mfma_f32_16x16x32_f16 v[92:95], v[142:145], v[198:201], v[92:95]
	v_mfma_f32_16x16x32_f16 v[88:91], v[150:153], v[198:201], v[88:91]
	v_mfma_f32_16x16x32_f16 v[76:79], v[142:145], v[206:209], v[76:79]
	v_mfma_f32_16x16x32_f16 v[72:75], v[150:153], v[206:209], v[72:75]
	v_mfma_f32_16x16x32_f16 v[126:129], v[146:149], v[186:189], v[126:129]
	v_mfma_f32_16x16x32_f16 v[122:125], v[154:157], v[186:189], v[122:125]
	v_mfma_f32_16x16x32_f16 v[110:113], v[146:149], v[194:197], v[110:113]
	v_mfma_f32_16x16x32_f16 v[106:109], v[154:157], v[194:197], v[106:109]
	v_mfma_f32_16x16x32_f16 v[92:95], v[146:149], v[202:205], v[92:95]
	v_mfma_f32_16x16x32_f16 v[88:91], v[154:157], v[202:205], v[88:91]
	v_mfma_f32_16x16x32_f16 v[76:79], v[146:149], v[216:219], v[76:79]
	v_mfma_f32_16x16x32_f16 v[72:75], v[154:157], v[216:219], v[72:75]
	v_mfma_f32_16x16x32_f16 v[118:121], v[158:161], v[182:185], v[118:121]
	v_mfma_f32_16x16x32_f16 v[114:117], v[168:171], v[182:185], v[114:117]
	v_mfma_f32_16x16x32_f16 v[102:105], v[158:161], v[190:193], v[102:105]
	v_mfma_f32_16x16x32_f16 v[98:101], v[168:171], v[190:193], v[98:101]
	v_mfma_f32_16x16x32_f16 v[84:87], v[158:161], v[198:201], v[84:87]
	v_mfma_f32_16x16x32_f16 v[80:83], v[168:171], v[198:201], v[80:83]
	v_mfma_f32_16x16x32_f16 v[68:71], v[158:161], v[206:209], v[68:71]
	v_mfma_f32_16x16x32_f16 v[64:67], v[168:171], v[206:209], v[64:67]
	v_mfma_f32_16x16x32_f16 v[118:121], v[162:165], v[186:189], v[118:121]
	v_mfma_f32_16x16x32_f16 v[114:117], v[178:181], v[186:189], v[114:117]
	v_mfma_f32_16x16x32_f16 v[102:105], v[162:165], v[194:197], v[102:105]
	v_mfma_f32_16x16x32_f16 v[98:101], v[178:181], v[194:197], v[98:101]
	v_mfma_f32_16x16x32_f16 v[84:87], v[162:165], v[202:205], v[84:87]
	v_mfma_f32_16x16x32_f16 v[80:83], v[178:181], v[202:205], v[80:83]
	v_mfma_f32_16x16x32_f16 v[68:71], v[162:165], v[216:219], v[68:71]
	v_mfma_f32_16x16x32_f16 v[64:67], v[178:181], v[216:219], v[64:67]
	s_setprio 0
	s_barrier
	s_add_i32 s84, s84, s76
	v_lshl_add_u64 v[172:173], vcc, 0, v[96:97]
	s_mov_b32 m0, s84
	ds_read_b128 v[182:185], v177 offset:16384
	ds_read_b128 v[186:189], v177 offset:17408
	ds_read_b128 v[190:193], v177 offset:18432
	ds_read_b128 v[194:197], v177 offset:19456
	ds_read_b128 v[198:201], v177 offset:20480
	ds_read_b128 v[202:205], v177 offset:21504
	ds_read_b128 v[206:209], v177 offset:22528
	ds_read_b128 v[216:219], v177 offset:23552
	global_load_lds_dwordx4 v[172:173], off
	s_add_i32 m0, s84, 0x2000
	v_lshl_add_u64 v[210:211], vcc, 0, v[134:135]
	s_add_u32 vcc_lo, vcc_lo, s71
	s_addc_u32 vcc_hi, vcc_hi, 0
	s_add_i32 s57, s57, s76
	global_load_lds_dwordx4 v[210:211], off
	v_lshl_add_u64 v[212:213], vcc, 0, v[96:97]
	s_mov_b32 m0, s57
	v_lshl_add_u64 v[220:221], vcc, 0, v[134:135]
	global_load_lds_dwordx4 v[212:213], off
	s_add_i32 m0, s57, 0x2000
	v_lshl_add_u64 v[222:223], s[36:37], 0, v[130:131]
	global_load_lds_dwordx4 v[220:221], off
	s_mov_b32 m0, s77
	v_lshl_add_u64 v[224:225], s[36:37], 0, v[132:133]
	global_load_lds_dwordx4 v[222:223], off
	s_mov_b32 m0, s78
	s_nop 0
	global_load_lds_dwordx4 v[224:225], off
	s_waitcnt vmcnt(8)
	s_waitcnt lgkmcnt(0)
	s_barrier
	s_setprio 1
	s_waitcnt lgkmcnt(0)
	v_mfma_f32_16x16x32_f16 v[60:63], v[142:145], v[182:185], v[60:63]
	v_mfma_f32_16x16x32_f16 v[56:59], v[150:153], v[182:185], v[56:59]
	v_mfma_f32_16x16x32_f16 v[44:47], v[142:145], v[190:193], v[44:47]
	v_mfma_f32_16x16x32_f16 v[40:43], v[150:153], v[190:193], v[40:43]
	v_mfma_f32_16x16x32_f16 v[28:31], v[142:145], v[198:201], v[28:31]
	v_mfma_f32_16x16x32_f16 v[24:27], v[150:153], v[198:201], v[24:27]
	v_mfma_f32_16x16x32_f16 v[12:15], v[142:145], v[206:209], v[12:15]
	v_mfma_f32_16x16x32_f16 v[8:11], v[150:153], v[206:209], v[8:11]
	v_mfma_f32_16x16x32_f16 v[60:63], v[146:149], v[186:189], v[60:63]
	v_mfma_f32_16x16x32_f16 v[56:59], v[154:157], v[186:189], v[56:59]
	v_mfma_f32_16x16x32_f16 v[44:47], v[146:149], v[194:197], v[44:47]
	v_mfma_f32_16x16x32_f16 v[40:43], v[154:157], v[194:197], v[40:43]
	v_mfma_f32_16x16x32_f16 v[28:31], v[146:149], v[202:205], v[28:31]
	v_mfma_f32_16x16x32_f16 v[24:27], v[154:157], v[202:205], v[24:27]
	v_mfma_f32_16x16x32_f16 v[12:15], v[146:149], v[216:219], v[12:15]
	v_mfma_f32_16x16x32_f16 v[8:11], v[154:157], v[216:219], v[8:11]
	v_mfma_f32_16x16x32_f16 v[52:55], v[158:161], v[182:185], v[52:55]
	v_mfma_f32_16x16x32_f16 v[48:51], v[168:171], v[182:185], v[48:51]
	v_mfma_f32_16x16x32_f16 v[36:39], v[158:161], v[190:193], v[36:39]
	v_mfma_f32_16x16x32_f16 v[32:35], v[168:171], v[190:193], v[32:35]
	v_mfma_f32_16x16x32_f16 v[20:23], v[158:161], v[198:201], v[20:23]
	v_mfma_f32_16x16x32_f16 v[16:19], v[168:171], v[198:201], v[16:19]
	v_mfma_f32_16x16x32_f16 v[4:7], v[158:161], v[206:209], v[4:7]
	v_mfma_f32_16x16x32_f16 v[0:3], v[168:171], v[206:209], v[0:3]
	v_mfma_f32_16x16x32_f16 v[52:55], v[162:165], v[186:189], v[52:55]
	v_mfma_f32_16x16x32_f16 v[48:51], v[178:181], v[186:189], v[48:51]
	v_mfma_f32_16x16x32_f16 v[36:39], v[162:165], v[194:197], v[36:39]
	v_mfma_f32_16x16x32_f16 v[32:35], v[178:181], v[194:197], v[32:35]
	v_mfma_f32_16x16x32_f16 v[20:23], v[162:165], v[202:205], v[20:23]
	v_mfma_f32_16x16x32_f16 v[16:19], v[178:181], v[202:205], v[16:19]
	v_mfma_f32_16x16x32_f16 v[4:7], v[162:165], v[216:219], v[4:7]
	v_mfma_f32_16x16x32_f16 v[0:3], v[178:181], v[216:219], v[0:3]
	s_setprio 0
	s_barrier
	s_add_i32 s57, 0, 0x18000
	s_add_i32 s84, 0, 0x1c000
	v_add_u32_e32 v154, s57, v174
	v_add_u32_e32 v178, s84, v174
	ds_read_b128 v[142:145], v154
	ds_read_b128 v[146:149], v154 offset:1024
	ds_read_b128 v[150:153], v154 offset:2048
	ds_read_b128 v[154:157], v154 offset:3072
	ds_read_b128 v[158:161], v178
	ds_read_b128 v[162:165], v178 offset:1024
	ds_read_b128 v[168:171], v178 offset:2048
	ds_read_b128 v[178:181], v178 offset:3072
	s_add_u32 s36, s36, s20
	s_addc_u32 s37, s37, 0
	s_mov_b32 m0, s79
	v_lshl_add_u64 v[226:227], s[36:37], 0, v[130:131]
	ds_read_b128 v[182:185], v177 offset:32768
	ds_read_b128 v[186:189], v177 offset:33792
	ds_read_b128 v[190:193], v177 offset:34816
	ds_read_b128 v[194:197], v177 offset:35840
	ds_read_b128 v[198:201], v177 offset:36864
	ds_read_b128 v[202:205], v177 offset:37888
	ds_read_b128 v[206:209], v177 offset:38912
	ds_read_b128 v[216:219], v177 offset:39936
	global_load_lds_dwordx4 v[226:227], off
	v_lshl_add_u64 v[226:227], s[36:37], 0, v[132:133]
	s_mov_b32 m0, s80
	s_nop 0
	global_load_lds_dwordx4 v[226:227], off
	s_waitcnt vmcnt(8)
	s_waitcnt lgkmcnt(0)
	s_barrier
	s_setprio 1
	s_waitcnt lgkmcnt(0)
	v_mfma_f32_16x16x32_f16 v[126:129], v[142:145], v[182:185], v[126:129]
	v_mfma_f32_16x16x32_f16 v[122:125], v[150:153], v[182:185], v[122:125]
	v_mfma_f32_16x16x32_f16 v[110:113], v[142:145], v[190:193], v[110:113]
	v_mfma_f32_16x16x32_f16 v[106:109], v[150:153], v[190:193], v[106:109]
	v_mfma_f32_16x16x32_f16 v[92:95], v[142:145], v[198:201], v[92:95]
	v_mfma_f32_16x16x32_f16 v[88:91], v[150:153], v[198:201], v[88:91]
	v_mfma_f32_16x16x32_f16 v[76:79], v[142:145], v[206:209], v[76:79]
	v_mfma_f32_16x16x32_f16 v[72:75], v[150:153], v[206:209], v[72:75]
	v_mfma_f32_16x16x32_f16 v[126:129], v[146:149], v[186:189], v[126:129]
	v_mfma_f32_16x16x32_f16 v[122:125], v[154:157], v[186:189], v[122:125]
	v_mfma_f32_16x16x32_f16 v[110:113], v[146:149], v[194:197], v[110:113]
	v_mfma_f32_16x16x32_f16 v[106:109], v[154:157], v[194:197], v[106:109]
	v_mfma_f32_16x16x32_f16 v[92:95], v[146:149], v[202:205], v[92:95]
	v_mfma_f32_16x16x32_f16 v[88:91], v[154:157], v[202:205], v[88:91]
	v_mfma_f32_16x16x32_f16 v[76:79], v[146:149], v[216:219], v[76:79]
	v_mfma_f32_16x16x32_f16 v[72:75], v[154:157], v[216:219], v[72:75]
	v_mfma_f32_16x16x32_f16 v[118:121], v[158:161], v[182:185], v[118:121]
	v_mfma_f32_16x16x32_f16 v[114:117], v[168:171], v[182:185], v[114:117]
	v_mfma_f32_16x16x32_f16 v[102:105], v[158:161], v[190:193], v[102:105]
	v_mfma_f32_16x16x32_f16 v[98:101], v[168:171], v[190:193], v[98:101]
	v_mfma_f32_16x16x32_f16 v[84:87], v[158:161], v[198:201], v[84:87]
	v_mfma_f32_16x16x32_f16 v[80:83], v[168:171], v[198:201], v[80:83]
	v_mfma_f32_16x16x32_f16 v[68:71], v[158:161], v[206:209], v[68:71]
	v_mfma_f32_16x16x32_f16 v[64:67], v[168:171], v[206:209], v[64:67]
	v_mfma_f32_16x16x32_f16 v[118:121], v[162:165], v[186:189], v[118:121]
	v_mfma_f32_16x16x32_f16 v[114:117], v[178:181], v[186:189], v[114:117]
	v_mfma_f32_16x16x32_f16 v[102:105], v[162:165], v[194:197], v[102:105]
	v_mfma_f32_16x16x32_f16 v[98:101], v[178:181], v[194:197], v[98:101]
	v_mfma_f32_16x16x32_f16 v[84:87], v[162:165], v[202:205], v[84:87]
	v_mfma_f32_16x16x32_f16 v[80:83], v[178:181], v[202:205], v[80:83]
	v_mfma_f32_16x16x32_f16 v[68:71], v[162:165], v[216:219], v[68:71]
	v_mfma_f32_16x16x32_f16 v[64:67], v[178:181], v[216:219], v[64:67]
	s_setprio 0
	s_barrier
	s_add_i32 s36, s57, s76
	v_lshl_add_u64 v[172:173], v[172:173], 0, s[94:95]
	s_mov_b32 m0, s36
	ds_read_b128 v[182:185], v177 offset:49152
	ds_read_b128 v[186:189], v177 offset:50176
	ds_read_b128 v[190:193], v177 offset:51200
	ds_read_b128 v[194:197], v177 offset:52224
	ds_read_b128 v[198:201], v177 offset:53248
	ds_read_b128 v[202:205], v177 offset:54272
	ds_read_b128 v[206:209], v177 offset:55296
	ds_read_b128 v[216:219], v177 offset:56320
	global_load_lds_dwordx4 v[172:173], off
	v_lshl_add_u64 v[172:173], v[210:211], 0, s[94:95]
	s_add_i32 m0, s36, 0x2000
	s_add_i32 s36, s84, s76
	global_load_lds_dwordx4 v[172:173], off
	v_lshl_add_u64 v[172:173], v[212:213], 0, s[94:95]
	s_mov_b32 m0, s36
	s_nop 0
	global_load_lds_dwordx4 v[172:173], off
	v_lshl_add_u64 v[172:173], v[220:221], 0, s[94:95]
	s_add_i32 m0, s36, 0x2000
	s_nop 0
	global_load_lds_dwordx4 v[172:173], off
	v_lshl_add_u64 v[172:173], v[222:223], 0, s[94:95]
	s_mov_b32 m0, s81
	s_nop 0
	global_load_lds_dwordx4 v[172:173], off
	v_lshl_add_u64 v[172:173], v[224:225], 0, s[94:95]
	s_mov_b32 m0, s99
	s_nop 0
	global_load_lds_dwordx4 v[172:173], off
	s_waitcnt vmcnt(8)
	s_waitcnt lgkmcnt(0)
	s_barrier
	s_setprio 1
	s_waitcnt lgkmcnt(0)
	v_mfma_f32_16x16x32_f16 v[60:63], v[142:145], v[182:185], v[60:63]
	v_mfma_f32_16x16x32_f16 v[56:59], v[150:153], v[182:185], v[56:59]
	v_mfma_f32_16x16x32_f16 v[44:47], v[142:145], v[190:193], v[44:47]
	v_mfma_f32_16x16x32_f16 v[40:43], v[150:153], v[190:193], v[40:43]
	v_mfma_f32_16x16x32_f16 v[28:31], v[142:145], v[198:201], v[28:31]
	v_mfma_f32_16x16x32_f16 v[24:27], v[150:153], v[198:201], v[24:27]
	v_mfma_f32_16x16x32_f16 v[12:15], v[142:145], v[206:209], v[12:15]
	v_mfma_f32_16x16x32_f16 v[8:11], v[150:153], v[206:209], v[8:11]
	v_mfma_f32_16x16x32_f16 v[60:63], v[146:149], v[186:189], v[60:63]
	v_mfma_f32_16x16x32_f16 v[56:59], v[154:157], v[186:189], v[56:59]
	v_mfma_f32_16x16x32_f16 v[44:47], v[146:149], v[194:197], v[44:47]
	v_mfma_f32_16x16x32_f16 v[40:43], v[154:157], v[194:197], v[40:43]
	v_mfma_f32_16x16x32_f16 v[28:31], v[146:149], v[202:205], v[28:31]
	v_mfma_f32_16x16x32_f16 v[24:27], v[154:157], v[202:205], v[24:27]
	v_mfma_f32_16x16x32_f16 v[12:15], v[146:149], v[216:219], v[12:15]
	v_mfma_f32_16x16x32_f16 v[8:11], v[154:157], v[216:219], v[8:11]
	v_mfma_f32_16x16x32_f16 v[52:55], v[158:161], v[182:185], v[52:55]
	v_mfma_f32_16x16x32_f16 v[48:51], v[168:171], v[182:185], v[48:51]
	v_mfma_f32_16x16x32_f16 v[36:39], v[158:161], v[190:193], v[36:39]
	v_mfma_f32_16x16x32_f16 v[32:35], v[168:171], v[190:193], v[32:35]
	v_mfma_f32_16x16x32_f16 v[20:23], v[158:161], v[198:201], v[20:23]
	v_mfma_f32_16x16x32_f16 v[16:19], v[168:171], v[198:201], v[16:19]
	v_mfma_f32_16x16x32_f16 v[4:7], v[158:161], v[206:209], v[4:7]
	v_mfma_f32_16x16x32_f16 v[0:3], v[168:171], v[206:209], v[0:3]
	v_mfma_f32_16x16x32_f16 v[52:55], v[162:165], v[186:189], v[52:55]
	v_mfma_f32_16x16x32_f16 v[48:51], v[178:181], v[186:189], v[48:51]
	v_mfma_f32_16x16x32_f16 v[36:39], v[162:165], v[194:197], v[36:39]
	v_mfma_f32_16x16x32_f16 v[32:35], v[178:181], v[194:197], v[32:35]
	v_mfma_f32_16x16x32_f16 v[20:23], v[162:165], v[202:205], v[20:23]
	v_mfma_f32_16x16x32_f16 v[16:19], v[178:181], v[202:205], v[16:19]
	v_mfma_f32_16x16x32_f16 v[4:7], v[162:165], v[216:219], v[4:7]
	v_mfma_f32_16x16x32_f16 v[0:3], v[178:181], v[216:219], v[0:3]
	s_setprio 0
	s_barrier
	s_add_u32 s34, s34, 0x100
	s_addc_u32 s35, s35, 0
	s_add_u32 s46, s46, 0x100
	s_addc_u32 s47, s47, 0
	s_cmp_ge_u32 s56, s70
	s_mov_b32 s36, s56
	s_cbranch_scc0 .LBB0_654
	s_and_b64 vcc, exec, s[26:27]
	s_cbranch_vccz .LBB0_657
	s_barrier
